# v016 + nt (non-temporal) loads of the once-read f32 weights and x/mem rows in the prologue
# speedup vs baseline: 1.0042x; 1.0042x over previous
; __device__ __forceinline__ void tr_loads(const TrDesc& d, float (&wv)[32], int lane) {
; #pragma unroll
;     for (int i = 0; i < 32; ++i) wv[i] = d.W[(size_t)(d.k0 + 2 * i + (lane >> 5)) * d.N + d.n0 + (lane & 31)];
; }
.LBB0_370:
	s_ashr_i32 s51, s50, 31
	s_lshl_b64 s[50:51], s[50:51], 2
	v_add_u32_e32 v48, s38, v3
	s_add_u32 s30, s30, s50
	s_addc_u32 s31, s31, s51
	v_mov_b32_e32 v5, v1
	v_ashrrev_i32_e32 v49, 31, v48
	v_lshl_add_u64 v[6:7], s[30:31], 0, v[4:5]
	v_mul_lo_u32 v10, s44, v49
	v_mul_lo_u32 v11, s45, v48
	v_mad_u64_u32 v[8:9], s[30:31], s44, v48, 0
	v_add3_u32 v9, v9, v10, v11
	v_add_u32_e32 v10, 2, v48
	v_ashrrev_i32_e32 v11, 31, v10
	v_mul_lo_u32 v12, s44, v11
	v_mul_lo_u32 v13, s45, v10
	v_mad_u64_u32 v[10:11], s[30:31], s44, v10, 0
	v_add3_u32 v11, v11, v12, v13
	v_add_u32_e32 v12, 4, v48
	v_ashrrev_i32_e32 v13, 31, v12
	v_mul_lo_u32 v14, s44, v13
	v_mul_lo_u32 v15, s45, v12
	v_mad_u64_u32 v[12:13], s[30:31], s44, v12, 0
	v_add3_u32 v13, v13, v14, v15
	v_add_u32_e32 v14, 6, v48
	v_ashrrev_i32_e32 v15, 31, v14
	v_mul_lo_u32 v16, s44, v15
	v_mul_lo_u32 v17, s45, v14
	v_mad_u64_u32 v[14:15], s[30:31], s44, v14, 0
	v_add3_u32 v15, v15, v16, v17
	v_lshl_add_u64 v[16:17], v[14:15], 2, v[6:7]
	v_add_u32_e32 v14, 8, v48
	v_ashrrev_i32_e32 v15, 31, v14
	v_mul_lo_u32 v18, s44, v15
	v_mul_lo_u32 v19, s45, v14
	v_mad_u64_u32 v[14:15], s[30:31], s44, v14, 0
	v_add3_u32 v15, v15, v18, v19
	v_lshl_add_u64 v[20:21], v[14:15], 2, v[6:7]
	v_add_u32_e32 v14, 10, v48
	v_ashrrev_i32_e32 v15, 31, v14
	v_mul_lo_u32 v18, s44, v15
	v_mul_lo_u32 v19, s45, v14
	v_mad_u64_u32 v[14:15], s[30:31], s44, v14, 0
	v_add3_u32 v15, v15, v18, v19
	v_lshl_add_u64 v[22:23], v[14:15], 2, v[6:7]
	v_add_u32_e32 v14, 12, v48
	v_ashrrev_i32_e32 v15, 31, v14
	v_mul_lo_u32 v18, s44, v15
	v_mul_lo_u32 v19, s45, v14
	v_mad_u64_u32 v[14:15], s[30:31], s44, v14, 0
	v_add3_u32 v15, v15, v18, v19
	v_lshl_add_u64 v[24:25], v[14:15], 2, v[6:7]
	v_add_u32_e32 v14, 14, v48
	v_ashrrev_i32_e32 v15, 31, v14
	v_mul_lo_u32 v18, s44, v15
	v_mul_lo_u32 v19, s45, v14
	v_mad_u64_u32 v[14:15], s[30:31], s44, v14, 0
	v_lshl_add_u64 v[8:9], v[8:9], 2, v[6:7]
	v_add3_u32 v15, v15, v18, v19
	v_lshl_add_u64 v[10:11], v[10:11], 2, v[6:7]
	v_lshl_add_u64 v[12:13], v[12:13], 2, v[6:7]
	v_lshl_add_u64 v[26:27], v[14:15], 2, v[6:7]
	global_load_dword v14, v[8:9], off nt
	global_load_dword v15, v[10:11], off nt
	global_load_dword v18, v[12:13], off nt
	global_load_dword v19, v[16:17], off nt
	s_nop 0
	global_load_dword v16, v[20:21], off nt
	global_load_dword v17, v[22:23], off nt
	s_nop 0
	global_load_dword v20, v[24:25], off nt
	global_load_dword v21, v[26:27], off nt
	v_add_u32_e32 v8, 16, v48
	v_ashrrev_i32_e32 v9, 31, v8
	v_mul_lo_u32 v10, s44, v9
	v_mul_lo_u32 v11, s45, v8
	v_mad_u64_u32 v[8:9], s[30:31], s44, v8, 0
	v_add3_u32 v9, v9, v10, v11
	v_add_u32_e32 v10, 18, v48
	v_ashrrev_i32_e32 v11, 31, v10
	v_mul_lo_u32 v12, s44, v11
	v_mul_lo_u32 v13, s45, v10
	v_mad_u64_u32 v[10:11], s[30:31], s44, v10, 0
	v_add3_u32 v11, v11, v12, v13
	v_add_u32_e32 v12, 20, v48
	v_ashrrev_i32_e32 v13, 31, v12
	v_mul_lo_u32 v22, s44, v13
	v_mul_lo_u32 v23, s45, v12
	v_mad_u64_u32 v[12:13], s[30:31], s44, v12, 0
	v_add3_u32 v13, v13, v22, v23
	v_add_u32_e32 v22, 22, v48
	v_ashrrev_i32_e32 v23, 31, v22
	v_mul_lo_u32 v24, s44, v23
	v_mul_lo_u32 v25, s45, v22
	v_mad_u64_u32 v[22:23], s[30:31], s44, v22, 0
	v_add3_u32 v23, v23, v24, v25
	v_add_u32_e32 v24, 24, v48
	v_ashrrev_i32_e32 v25, 31, v24
	v_mul_lo_u32 v26, s44, v25
	v_mul_lo_u32 v27, s45, v24
	v_mad_u64_u32 v[24:25], s[30:31], s44, v24, 0
	v_add3_u32 v25, v25, v26, v27
	v_add_u32_e32 v26, 26, v48
	v_ashrrev_i32_e32 v27, 31, v26
	v_mul_lo_u32 v28, s44, v27
	v_mul_lo_u32 v29, s45, v26
	v_mad_u64_u32 v[26:27], s[30:31], s44, v26, 0
	v_add3_u32 v27, v27, v28, v29
	v_add_u32_e32 v28, 28, v48
	v_ashrrev_i32_e32 v29, 31, v28
	v_mul_lo_u32 v30, s44, v29
	v_mul_lo_u32 v31, s45, v28
	v_mad_u64_u32 v[28:29], s[30:31], s44, v28, 0
	v_add3_u32 v29, v29, v30, v31
	v_add_u32_e32 v30, 30, v48
	v_ashrrev_i32_e32 v31, 31, v30
	v_mul_lo_u32 v32, s44, v31
	v_mul_lo_u32 v33, s45, v30
	v_mad_u64_u32 v[30:31], s[30:31], s44, v30, 0
	v_lshl_add_u64 v[8:9], v[8:9], 2, v[6:7]
	v_add3_u32 v31, v31, v32, v33
	v_lshl_add_u64 v[10:11], v[10:11], 2, v[6:7]
	v_lshl_add_u64 v[12:13], v[12:13], 2, v[6:7]
	v_lshl_add_u64 v[22:23], v[22:23], 2, v[6:7]
	v_lshl_add_u64 v[24:25], v[24:25], 2, v[6:7]
	v_lshl_add_u64 v[26:27], v[26:27], 2, v[6:7]
	v_lshl_add_u64 v[28:29], v[28:29], 2, v[6:7]
	v_lshl_add_u64 v[38:39], v[30:31], 2, v[6:7]
	global_load_dword v30, v[8:9], off nt
	global_load_dword v31, v[10:11], off nt
	global_load_dword v34, v[12:13], off nt
	global_load_dword v35, v[22:23], off nt
	global_load_dword v32, v[24:25], off nt
	global_load_dword v33, v[26:27], off nt
	global_load_dword v36, v[28:29], off nt
	global_load_dword v37, v[38:39], off nt
	v_add_u32_e32 v8, 32, v48
	v_ashrrev_i32_e32 v9, 31, v8
	v_mul_lo_u32 v10, s44, v9
	v_mul_lo_u32 v11, s45, v8
	v_mad_u64_u32 v[8:9], s[30:31], s44, v8, 0
	v_add3_u32 v9, v9, v10, v11
	v_add_u32_e32 v10, 34, v48
	v_ashrrev_i32_e32 v11, 31, v10
	v_mul_lo_u32 v12, s44, v11
	v_mul_lo_u32 v13, s45, v10
	v_mad_u64_u32 v[10:11], s[30:31], s44, v10, 0
	v_add3_u32 v11, v11, v12, v13
	v_add_u32_e32 v12, 36, v48
	v_ashrrev_i32_e32 v13, 31, v12
	v_mul_lo_u32 v22, s44, v13
	v_mul_lo_u32 v23, s45, v12
	v_mad_u64_u32 v[12:13], s[30:31], s44, v12, 0
	v_add3_u32 v13, v13, v22, v23
	v_add_u32_e32 v22, 38, v48
	v_ashrrev_i32_e32 v23, 31, v22
	v_mul_lo_u32 v24, s44, v23
	v_mul_lo_u32 v25, s45, v22
	v_mad_u64_u32 v[22:23], s[30:31], s44, v22, 0
	v_add3_u32 v23, v23, v24, v25
	v_add_u32_e32 v24, 40, v48
	v_ashrrev_i32_e32 v25, 31, v24
	v_mul_lo_u32 v26, s44, v25
	v_mul_lo_u32 v27, s45, v24
	v_mad_u64_u32 v[24:25], s[30:31], s44, v24, 0
	v_add3_u32 v25, v25, v26, v27
; __device__ __forceinline__ void tr_loads(const TrDesc& d, float (&wv)[32], int lane) {
; #pragma unroll
;     for (int i = 0; i < 32; ++i) wv[i] = d.W[(size_t)(d.k0 + 2 * i + (lane >> 5)) * d.N + d.n0 + (lane & 31)];
; }
	v_add_u32_e32 v26, 42, v48
	v_ashrrev_i32_e32 v27, 31, v26
	v_mul_lo_u32 v28, s44, v27
	v_mul_lo_u32 v29, s45, v26
	v_mad_u64_u32 v[26:27], s[30:31], s44, v26, 0
	v_add3_u32 v27, v27, v28, v29
	v_add_u32_e32 v28, 44, v48
	v_ashrrev_i32_e32 v29, 31, v28
	v_mul_lo_u32 v38, s44, v29
	v_mul_lo_u32 v39, s45, v28
	v_mad_u64_u32 v[28:29], s[30:31], s44, v28, 0
	v_add3_u32 v29, v29, v38, v39
	v_add_u32_e32 v38, 46, v48
	v_ashrrev_i32_e32 v39, 31, v38
	v_mul_lo_u32 v40, s44, v39
	v_mul_lo_u32 v41, s45, v38
	v_mad_u64_u32 v[38:39], s[30:31], s44, v38, 0
	v_lshl_add_u64 v[8:9], v[8:9], 2, v[6:7]
	v_add3_u32 v39, v39, v40, v41
	v_lshl_add_u64 v[10:11], v[10:11], 2, v[6:7]
	v_lshl_add_u64 v[12:13], v[12:13], 2, v[6:7]
	v_lshl_add_u64 v[22:23], v[22:23], 2, v[6:7]
	v_lshl_add_u64 v[24:25], v[24:25], 2, v[6:7]
	v_lshl_add_u64 v[26:27], v[26:27], 2, v[6:7]
	v_lshl_add_u64 v[28:29], v[28:29], 2, v[6:7]
	v_lshl_add_u64 v[38:39], v[38:39], 2, v[6:7]
	global_load_dword v50, v[8:9], off nt
	global_load_dword v51, v[10:11], off nt
	global_load_dword v54, v[12:13], off nt
	global_load_dword v55, v[22:23], off nt
	global_load_dword v52, v[24:25], off nt
	global_load_dword v53, v[26:27], off nt
	global_load_dword v56, v[28:29], off nt
	global_load_dword v57, v[38:39], off nt
	v_add_u32_e32 v8, 48, v48
	v_ashrrev_i32_e32 v9, 31, v8
	v_mul_lo_u32 v10, s44, v9
	v_mul_lo_u32 v11, s45, v8
	v_mad_u64_u32 v[8:9], s[30:31], s44, v8, 0
	v_add3_u32 v9, v9, v10, v11
	v_add_u32_e32 v10, 50, v48
	v_ashrrev_i32_e32 v11, 31, v10
	v_mul_lo_u32 v12, s44, v11
	v_mul_lo_u32 v13, s45, v10
	v_mad_u64_u32 v[10:11], s[30:31], s44, v10, 0
	v_add3_u32 v11, v11, v12, v13
	v_add_u32_e32 v12, 52, v48
	v_ashrrev_i32_e32 v13, 31, v12
	v_mul_lo_u32 v22, s44, v13
	v_mul_lo_u32 v23, s45, v12
	v_mad_u64_u32 v[12:13], s[30:31], s44, v12, 0
	v_add3_u32 v13, v13, v22, v23
	v_add_u32_e32 v22, 54, v48
	v_ashrrev_i32_e32 v23, 31, v22
	v_mul_lo_u32 v24, s44, v23
	v_mul_lo_u32 v25, s45, v22
	v_mad_u64_u32 v[22:23], s[30:31], s44, v22, 0
	v_add3_u32 v23, v23, v24, v25
	v_add_u32_e32 v24, 56, v48
	v_ashrrev_i32_e32 v25, 31, v24
	v_mul_lo_u32 v26, s44, v25
	v_mul_lo_u32 v27, s45, v24
	v_mad_u64_u32 v[24:25], s[30:31], s44, v24, 0
	v_add3_u32 v25, v25, v26, v27
	v_add_u32_e32 v26, 58, v48
	v_ashrrev_i32_e32 v27, 31, v26
	v_mul_lo_u32 v28, s44, v27
	v_mul_lo_u32 v29, s45, v26
	v_mad_u64_u32 v[26:27], s[30:31], s44, v26, 0
	v_add3_u32 v27, v27, v28, v29
	v_add_u32_e32 v28, 60, v48
	v_ashrrev_i32_e32 v29, 31, v28
	v_mul_lo_u32 v38, s44, v29
	v_mul_lo_u32 v39, s45, v28
	v_mad_u64_u32 v[28:29], s[30:31], s44, v28, 0
	v_add3_u32 v29, v29, v38, v39
	v_add_u32_e32 v38, 62, v48
	v_ashrrev_i32_e32 v39, 31, v38
	v_mul_lo_u32 v40, s44, v39
	v_mul_lo_u32 v41, s45, v38
	v_mad_u64_u32 v[38:39], s[30:31], s44, v38, 0
	s_ashr_i32 s55, s54, 31
	v_add3_u32 v39, v39, v40, v41
	s_lshl_b64 s[30:31], s[54:55], 2
	v_lshl_add_u64 v[8:9], v[8:9], 2, v[6:7]
	v_lshl_add_u64 v[10:11], v[10:11], 2, v[6:7]
	v_lshl_add_u64 v[12:13], v[12:13], 2, v[6:7]
	v_lshl_add_u64 v[22:23], v[22:23], 2, v[6:7]
	v_lshl_add_u64 v[24:25], v[24:25], 2, v[6:7]
	v_lshl_add_u64 v[26:27], v[26:27], 2, v[6:7]
	v_lshl_add_u64 v[28:29], v[28:29], 2, v[6:7]
	v_lshl_add_u64 v[6:7], v[38:39], 2, v[6:7]
	v_add_u32_e32 v38, s82, v3
	s_add_u32 s30, s48, s30
	s_addc_u32 s31, s49, s31
	v_ashrrev_i32_e32 v39, 31, v38
	global_load_dword v66, v[8:9], off nt
	global_load_dword v67, v[10:11], off nt
	global_load_dword v72, v[12:13], off nt
	global_load_dword v73, v[22:23], off nt
	global_load_dword v70, v[24:25], off nt
	global_load_dword v71, v[26:27], off nt
	global_load_dword v68, v[28:29], off nt
	global_load_dword v69, v[6:7], off nt
	v_lshl_add_u64 v[58:59], s[30:31], 0, v[4:5]
	v_mul_lo_u32 v5, s46, v39
	v_mul_lo_u32 v8, s47, v38
	v_mad_u64_u32 v[6:7], s[30:31], s46, v38, 0
	v_add3_u32 v7, v7, v5, v8
	v_add_u32_e32 v5, 2, v38
	v_ashrrev_i32_e32 v8, 31, v5
	v_mul_lo_u32 v10, s46, v8
	v_mul_lo_u32 v11, s47, v5
	v_mad_u64_u32 v[8:9], s[30:31], s46, v5, 0
	v_add_u32_e32 v5, 4, v38
	v_add3_u32 v9, v9, v10, v11
	v_ashrrev_i32_e32 v10, 31, v5
	v_mul_lo_u32 v12, s46, v10
	v_mul_lo_u32 v13, s47, v5
	v_mad_u64_u32 v[10:11], s[30:31], s46, v5, 0
	v_add_u32_e32 v5, 6, v38
	v_add3_u32 v11, v11, v12, v13
	v_ashrrev_i32_e32 v12, 31, v5
	v_mul_lo_u32 v22, s46, v12
	v_mul_lo_u32 v23, s47, v5
	v_mad_u64_u32 v[12:13], s[30:31], s46, v5, 0
	v_add_u32_e32 v5, 8, v38
	v_add3_u32 v13, v13, v22, v23
	v_ashrrev_i32_e32 v22, 31, v5
	v_mul_lo_u32 v24, s46, v22
	v_mul_lo_u32 v25, s47, v5
	v_mad_u64_u32 v[22:23], s[30:31], s46, v5, 0
	v_add_u32_e32 v5, 10, v38
	v_add3_u32 v23, v23, v24, v25
	v_ashrrev_i32_e32 v24, 31, v5
	v_mul_lo_u32 v26, s46, v24
	v_mul_lo_u32 v27, s47, v5
	v_mad_u64_u32 v[24:25], s[30:31], s46, v5, 0
	v_add_u32_e32 v5, 12, v38
	v_add3_u32 v25, v25, v26, v27
	v_ashrrev_i32_e32 v26, 31, v5
	v_mul_lo_u32 v28, s46, v26
	v_mul_lo_u32 v29, s47, v5
	v_mad_u64_u32 v[26:27], s[30:31], s46, v5, 0
	v_add_u32_e32 v5, 14, v38
	v_add3_u32 v27, v27, v28, v29
	v_ashrrev_i32_e32 v28, 31, v5
	v_mul_lo_u32 v40, s46, v28
	v_mul_lo_u32 v41, s47, v5
	v_mad_u64_u32 v[28:29], s[30:31], s46, v5, 0
	v_lshl_add_u64 v[6:7], v[6:7], 2, v[58:59]
	v_lshl_add_u64 v[8:9], v[8:9], 2, v[58:59]
	v_lshl_add_u64 v[10:11], v[10:11], 2, v[58:59]
	v_lshl_add_u64 v[12:13], v[12:13], 2, v[58:59]
	v_lshl_add_u64 v[22:23], v[22:23], 2, v[58:59]
	v_add3_u32 v29, v29, v40, v41
	v_add_u32_e32 v5, 16, v38
	v_lshl_add_u64 v[24:25], v[24:25], 2, v[58:59]
	v_lshl_add_u64 v[26:27], v[26:27], 2, v[58:59]
	v_lshl_add_u64 v[28:29], v[28:29], 2, v[58:59]
	global_load_dword v7, v[6:7], off nt
	s_nop 0
	global_load_dword v6, v[8:9], off nt
; __device__ __forceinline__ void tr_loads(const TrDesc& d, float (&wv)[32], int lane) {
; #pragma unroll
;     for (int i = 0; i < 32; ++i) wv[i] = d.W[(size_t)(d.k0 + 2 * i + (lane >> 5)) * d.N + d.n0 + (lane & 31)];
; }
	s_nop 0
	global_load_dword v9, v[10:11], off nt
	global_load_dword v8, v[12:13], off nt
	s_nop 0
	global_load_dword v11, v[22:23], off nt
	global_load_dword v10, v[24:25], off nt
	global_load_dword v13, v[26:27], off nt
	global_load_dword v12, v[28:29], off nt
	v_ashrrev_i32_e32 v22, 31, v5
	v_mul_lo_u32 v24, s46, v22
	v_mul_lo_u32 v25, s47, v5
	v_mad_u64_u32 v[22:23], s[30:31], s46, v5, 0
	v_add_u32_e32 v5, 18, v38
	v_add3_u32 v23, v23, v24, v25
	v_ashrrev_i32_e32 v24, 31, v5
	v_mul_lo_u32 v26, s46, v24
	v_mul_lo_u32 v27, s47, v5
	v_mad_u64_u32 v[24:25], s[30:31], s46, v5, 0
	v_add_u32_e32 v5, 20, v38
	v_add3_u32 v25, v25, v26, v27
	v_ashrrev_i32_e32 v26, 31, v5
	v_mul_lo_u32 v28, s46, v26
	v_mul_lo_u32 v29, s47, v5
	v_mad_u64_u32 v[26:27], s[30:31], s46, v5, 0
	v_add_u32_e32 v5, 22, v38
	v_add3_u32 v27, v27, v28, v29
	v_ashrrev_i32_e32 v28, 31, v5
	v_mul_lo_u32 v40, s46, v28
	v_mul_lo_u32 v41, s47, v5
	v_mad_u64_u32 v[28:29], s[30:31], s46, v5, 0
	v_add_u32_e32 v5, 24, v38
	v_add3_u32 v29, v29, v40, v41
	v_ashrrev_i32_e32 v40, 31, v5
	v_mul_lo_u32 v42, s46, v40
	v_mul_lo_u32 v43, s47, v5
	v_mad_u64_u32 v[40:41], s[30:31], s46, v5, 0
	v_add_u32_e32 v5, 26, v38
	v_add3_u32 v41, v41, v42, v43
	v_ashrrev_i32_e32 v42, 31, v5
	v_mul_lo_u32 v44, s46, v42
	v_mul_lo_u32 v45, s47, v5
	v_mad_u64_u32 v[42:43], s[30:31], s46, v5, 0
	v_add_u32_e32 v5, 28, v38
	v_add3_u32 v43, v43, v44, v45
	v_ashrrev_i32_e32 v44, 31, v5
	v_mul_lo_u32 v46, s46, v44
	v_mul_lo_u32 v47, s47, v5
	v_mad_u64_u32 v[44:45], s[30:31], s46, v5, 0
	v_add_u32_e32 v5, 30, v38
	v_add3_u32 v45, v45, v46, v47
	v_ashrrev_i32_e32 v46, 31, v5
	v_mul_lo_u32 v60, s46, v46
	v_mul_lo_u32 v61, s47, v5
	v_mad_u64_u32 v[46:47], s[30:31], s46, v5, 0
	v_lshl_add_u64 v[22:23], v[22:23], 2, v[58:59]
	v_lshl_add_u64 v[24:25], v[24:25], 2, v[58:59]
	v_lshl_add_u64 v[26:27], v[26:27], 2, v[58:59]
	v_lshl_add_u64 v[28:29], v[28:29], 2, v[58:59]
	v_lshl_add_u64 v[40:41], v[40:41], 2, v[58:59]
	v_add3_u32 v47, v47, v60, v61
	v_add_u32_e32 v5, 32, v38
	v_lshl_add_u64 v[42:43], v[42:43], 2, v[58:59]
	v_lshl_add_u64 v[44:45], v[44:45], 2, v[58:59]
	v_lshl_add_u64 v[46:47], v[46:47], 2, v[58:59]
	global_load_dword v23, v[22:23], off nt
	s_nop 0
	global_load_dword v22, v[24:25], off nt
	s_nop 0
	global_load_dword v25, v[26:27], off nt
	global_load_dword v24, v[28:29], off nt
	s_nop 0
	global_load_dword v27, v[40:41], off nt
	global_load_dword v26, v[42:43], off nt
	global_load_dword v29, v[44:45], off nt
	global_load_dword v28, v[46:47], off nt
	v_ashrrev_i32_e32 v40, 31, v5
	v_mul_lo_u32 v42, s46, v40
	v_mul_lo_u32 v43, s47, v5
	v_mad_u64_u32 v[40:41], s[30:31], s46, v5, 0
	v_add_u32_e32 v5, 34, v38
	v_add3_u32 v41, v41, v42, v43
	v_ashrrev_i32_e32 v42, 31, v5
	v_mul_lo_u32 v44, s46, v42
	v_mul_lo_u32 v45, s47, v5
	v_mad_u64_u32 v[42:43], s[30:31], s46, v5, 0
	v_add_u32_e32 v5, 36, v38
	v_add3_u32 v43, v43, v44, v45
	v_ashrrev_i32_e32 v44, 31, v5
	v_mul_lo_u32 v46, s46, v44
	v_mul_lo_u32 v47, s47, v5
	v_mad_u64_u32 v[44:45], s[30:31], s46, v5, 0
	v_add_u32_e32 v5, 38, v38
	v_add3_u32 v45, v45, v46, v47
	v_ashrrev_i32_e32 v46, 31, v5
	v_mul_lo_u32 v60, s46, v46
	v_mul_lo_u32 v61, s47, v5
	v_mad_u64_u32 v[46:47], s[30:31], s46, v5, 0
	v_add_u32_e32 v5, 40, v38
	v_add3_u32 v47, v47, v60, v61
	v_ashrrev_i32_e32 v60, 31, v5
	v_mul_lo_u32 v62, s46, v60
	v_mul_lo_u32 v63, s47, v5
	v_mad_u64_u32 v[60:61], s[30:31], s46, v5, 0
	v_add_u32_e32 v5, 42, v38
	v_add3_u32 v61, v61, v62, v63
	v_ashrrev_i32_e32 v62, 31, v5
	v_mul_lo_u32 v64, s46, v62
	v_mul_lo_u32 v65, s47, v5
	v_mad_u64_u32 v[62:63], s[30:31], s46, v5, 0
	v_add_u32_e32 v5, 44, v38
	v_add3_u32 v63, v63, v64, v65
	v_ashrrev_i32_e32 v64, 31, v5
	v_mul_lo_u32 v80, s46, v64
	v_mul_lo_u32 v81, s47, v5
	v_mad_u64_u32 v[64:65], s[30:31], s46, v5, 0
	v_add_u32_e32 v5, 46, v38
	v_add3_u32 v65, v65, v80, v81
	v_ashrrev_i32_e32 v80, 31, v5
	s_waitcnt vmcnt(59)
	v_mul_lo_u32 v82, s46, v80
	v_mul_lo_u32 v83, s47, v5
	v_mad_u64_u32 v[80:81], s[30:31], s46, v5, 0
	v_lshl_add_u64 v[40:41], v[40:41], 2, v[58:59]
	v_lshl_add_u64 v[42:43], v[42:43], 2, v[58:59]
	v_lshl_add_u64 v[44:45], v[44:45], 2, v[58:59]
	v_lshl_add_u64 v[46:47], v[46:47], 2, v[58:59]
	v_lshl_add_u64 v[60:61], v[60:61], 2, v[58:59]
	v_add3_u32 v81, v81, v82, v83
	v_add_u32_e32 v5, 48, v38
	v_lshl_add_u64 v[62:63], v[62:63], 2, v[58:59]
	v_lshl_add_u64 v[64:65], v[64:65], 2, v[58:59]
	v_lshl_add_u64 v[80:81], v[80:81], 2, v[58:59]
	global_load_dword v41, v[40:41], off nt
	s_nop 0
	global_load_dword v40, v[42:43], off nt
	s_nop 0
	global_load_dword v43, v[44:45], off nt
	global_load_dword v42, v[46:47], off nt
	s_nop 0
	global_load_dword v45, v[60:61], off nt
	global_load_dword v44, v[62:63], off nt
	global_load_dword v47, v[64:65], off nt
	global_load_dword v46, v[80:81], off nt
	v_ashrrev_i32_e32 v60, 31, v5
	v_mul_lo_u32 v62, s46, v60
	v_mul_lo_u32 v63, s47, v5
	v_mad_u64_u32 v[60:61], s[30:31], s46, v5, 0
	v_add_u32_e32 v5, 50, v38
	v_add3_u32 v61, v61, v62, v63
	v_ashrrev_i32_e32 v62, 31, v5
	v_mul_lo_u32 v64, s46, v62
	v_mul_lo_u32 v65, s47, v5
	v_mad_u64_u32 v[62:63], s[30:31], s46, v5, 0
	v_add_u32_e32 v5, 52, v38
	v_add3_u32 v63, v63, v64, v65
	v_ashrrev_i32_e32 v64, 31, v5
	v_mul_lo_u32 v80, s46, v64
	v_mul_lo_u32 v81, s47, v5
	v_mad_u64_u32 v[64:65], s[30:31], s46, v5, 0
	v_add_u32_e32 v5, 54, v38
	v_add3_u32 v65, v65, v80, v81
	v_ashrrev_i32_e32 v80, 31, v5
	v_mul_lo_u32 v82, s46, v80
	v_mul_lo_u32 v83, s47, v5
	v_mad_u64_u32 v[80:81], s[30:31], s46, v5, 0
	v_add_u32_e32 v5, 56, v38
	v_add3_u32 v81, v81, v82, v83
	v_ashrrev_i32_e32 v82, 31, v5
	v_mul_lo_u32 v84, s46, v82
	v_mul_lo_u32 v85, s47, v5
	v_mad_u64_u32 v[82:83], s[30:31], s46, v5, 0
	v_add_u32_e32 v5, 58, v38
	v_add3_u32 v83, v83, v84, v85
	v_ashrrev_i32_e32 v84, 31, v5
	s_waitcnt vmcnt(62)
; #define LAS __attribute__((address_space(3)))
; __device__ __forceinline__ void tr_loads(const TrDesc& d, float (&wv)[32], int lane) {
;     ...
;     for (int i = 0; i < 32; ++i) wv[i] = d.W[(size_t)(d.k0 + 2 * i + (lane >> 5)) * d.N + d.n0 + (lane & 31)];
; }
; __device__ __forceinline__ void tr_finish(const TrDesc& d, float (&wv)[32], LAS float* scr, int lane) {
;     if (d.gain) {
; #pragma unroll
;         for (int i = 0; i < 32; ++i) wv[i] *= d.gain[d.k0 + 2 * i + (lane >> 5)];
	v_mul_lo_u32 v86, s46, v84
	v_mul_lo_u32 v87, s47, v5
	v_mad_u64_u32 v[84:85], s[30:31], s46, v5, 0
	v_add_u32_e32 v5, 60, v38
	v_add3_u32 v85, v85, v86, v87
	v_ashrrev_i32_e32 v86, 31, v5
	v_mul_lo_u32 v88, s46, v86
	v_mul_lo_u32 v89, s47, v5
	v_mad_u64_u32 v[86:87], s[30:31], s46, v5, 0
	v_add_u32_e32 v5, 62, v38
	v_add3_u32 v87, v87, v88, v89
	v_ashrrev_i32_e32 v88, 31, v5
	v_mul_lo_u32 v90, s46, v88
	v_mul_lo_u32 v91, s47, v5
	v_mad_u64_u32 v[88:89], s[30:31], s46, v5, 0
	v_lshl_add_u64 v[60:61], v[60:61], 2, v[58:59]
	v_lshl_add_u64 v[62:63], v[62:63], 2, v[58:59]
	v_lshl_add_u64 v[64:65], v[64:65], 2, v[58:59]
	v_add3_u32 v89, v89, v90, v91
	v_lshl_add_u64 v[80:81], v[80:81], 2, v[58:59]
	v_lshl_add_u64 v[82:83], v[82:83], 2, v[58:59]
	v_lshl_add_u64 v[84:85], v[84:85], 2, v[58:59]
	v_lshl_add_u64 v[86:87], v[86:87], 2, v[58:59]
	v_lshl_add_u64 v[88:89], v[88:89], 2, v[58:59]
	global_load_dword v59, v[60:61], off nt
	global_load_dword v58, v[62:63], off nt
	s_nop 0
	global_load_dword v61, v[64:65], off nt
	global_load_dword v60, v[80:81], off nt
	global_load_dword v63, v[82:83], off nt
	global_load_dword v62, v[84:85], off nt
	s_nop 0
	global_load_dword v65, v[86:87], off nt
	global_load_dword v64, v[88:89], off nt
	s_cmp_lg_u64 s[34:35], 0
	s_cbranch_scc0 .LBB0_372
	v_lshl_add_u64 v[48:49], v[48:49], 2, s[34:35]
	global_load_dword v80, v[48:49], off
	global_load_dword v81, v[48:49], off offset:8
	global_load_dword v82, v[48:49], off offset:16
	global_load_dword v83, v[48:49], off offset:24
	global_load_dword v84, v[48:49], off offset:32
	global_load_dword v85, v[48:49], off offset:40
	global_load_dword v86, v[48:49], off offset:48
	global_load_dword v87, v[48:49], off offset:56
	global_load_dword v88, v[48:49], off offset:64
	global_load_dword v89, v[48:49], off offset:72
	global_load_dword v90, v[48:49], off offset:80
	global_load_dword v91, v[48:49], off offset:88
	global_load_dword v92, v[48:49], off offset:96
	global_load_dword v93, v[48:49], off offset:104
	global_load_dword v94, v[48:49], off offset:112
	global_load_dword v95, v[48:49], off offset:120
	global_load_dword v96, v[48:49], off offset:128
	global_load_dword v97, v[48:49], off offset:136
	global_load_dword v98, v[48:49], off offset:144
	global_load_dword v99, v[48:49], off offset:152
	global_load_dword v100, v[48:49], off offset:160
	global_load_dword v101, v[48:49], off offset:168
	global_load_dword v102, v[48:49], off offset:176
	global_load_dword v103, v[48:49], off offset:184
	global_load_dword v104, v[48:49], off offset:192
	global_load_dword v105, v[48:49], off offset:200
	global_load_dword v106, v[48:49], off offset:208
	global_load_dword v107, v[48:49], off offset:216
	global_load_dword v108, v[48:49], off offset:224
	global_load_dword v109, v[48:49], off offset:232
	global_load_dword v110, v[48:49], off offset:240
	global_load_dword v111, v[48:49], off offset:248
	s_waitcnt vmcnt(30)
	v_pk_mul_f32 v[14:15], v[14:15], v[80:81]
	s_waitcnt vmcnt(28)
	v_pk_mul_f32 v[18:19], v[18:19], v[82:83]
	s_waitcnt vmcnt(26)
	v_pk_mul_f32 v[16:17], v[16:17], v[84:85]
	s_waitcnt vmcnt(24)
	v_pk_mul_f32 v[20:21], v[20:21], v[86:87]
	s_waitcnt vmcnt(22)
	v_pk_mul_f32 v[30:31], v[30:31], v[88:89]
	s_waitcnt vmcnt(20)
	v_pk_mul_f32 v[34:35], v[34:35], v[90:91]
	s_waitcnt vmcnt(18)
	v_pk_mul_f32 v[32:33], v[32:33], v[92:93]
	s_waitcnt vmcnt(16)
	v_pk_mul_f32 v[36:37], v[36:37], v[94:95]
	s_waitcnt vmcnt(14)
	v_pk_mul_f32 v[50:51], v[50:51], v[96:97]
	s_waitcnt vmcnt(12)
	v_pk_mul_f32 v[54:55], v[54:55], v[98:99]
	s_waitcnt vmcnt(10)
	v_pk_mul_f32 v[52:53], v[52:53], v[100:101]
	s_waitcnt vmcnt(8)
	v_pk_mul_f32 v[56:57], v[56:57], v[102:103]
	s_waitcnt vmcnt(6)
	v_pk_mul_f32 v[66:67], v[66:67], v[104:105]
	s_waitcnt vmcnt(4)
	v_pk_mul_f32 v[72:73], v[72:73], v[106:107]
	s_waitcnt vmcnt(2)
	v_pk_mul_f32 v[70:71], v[70:71], v[108:109]
	s_waitcnt vmcnt(0)
	v_pk_mul_f32 v[68:69], v[68:69], v[110:111]

; __device__ __forceinline__ unsigned pk_bf16(float lo, float hi) { f32x2 v = {lo, hi}; bf16x2_t b = __builtin_convertvector(v, bf16x2_t); return __builtin_bit_cast(unsigned, b); }
; __device__ __forceinline__ void prologue(const Params& p, LAS unsigned char* lds, int gw, int NGW, int wave, int lane) {
;     ...
;     for (int m = gw; m < AROWS; m += 2 * NGW) {
;         const int m2 = m + NGW; const bool two = m2 < AROWS;
;         const float* s1 = m < T ? p.in[0] + (size_t)m * DM : p.in[1] + (size_t)(m - T) * DM;
;         const float* s2 = !two ? s1 : (m2 < T ? p.in[0] + (size_t)m2 * DM : p.in[1] + (size_t)(m2 - T) * DM);
;         const f32x4* x1 = (const f32x4*)s1 + lane; const f32x4* x2 = (const f32x4*)s2 + lane;
;         f32x4 a[4], b[4];
; #pragma unroll
;         for (int j = 0; j < 4; ++j) { a[j] = x1[64 * j]; b[j] = x2[64 * j]; }
;         float sa = 0.f, sb = 0.f;
; #pragma unroll
;         for (int j = 0; j < 4; ++j) { sa += (a[j].x * a[j].x + a[j].y * a[j].y) + (a[j].z * a[j].z + a[j].w * a[j].w); sb += (b[j].x * b[j].x + b[j].y * b[j].y) + (b[j].z * b[j].z + b[j].w * b[j].w); }
;         sa = wave_sum(sa); sb = wave_sum(sb);
;         u32x2* o1 = (u32x2*)(xb + (size_t)m * DM) + lane;
; #pragma unroll
;         for (int j = 0; j < 4; ++j) { u32x2 w; w.x = pk_bf16(a[j].x, a[j].y); w.y = pk_bf16(a[j].z, a[j].w); o1[64 * j] = w; }
;         if (lane < 4) ssq[(size_t)m * 4 + lane] = lane == 0 ? sa : 0.f;
.LBB0_385:
	global_load_dwordx4 v[28:31], v0, s[14:15] nt
	global_load_dwordx4 v[14:17], v0, s[16:17] nt
	global_load_dwordx4 v[32:35], v0, s[14:15] offset:1024 nt
	global_load_dwordx4 v[10:13], v0, s[16:17] offset:1024 nt
	global_load_dwordx4 v[36:39], v0, s[14:15] offset:2048 nt
	global_load_dwordx4 v[6:9], v0, s[16:17] offset:2048 nt
	global_load_dwordx4 v[40:43], v0, s[14:15] offset:3072 nt
	global_load_dwordx4 v[2:5], v0, s[16:17] offset:3072 nt
	s_lshl_b64 s[14:15], s[2:3], 11
	s_waitcnt vmcnt(7)
	v_mul_f32_e32 v44, v29, v29
	v_mul_f32_e32 v45, v31, v31
	s_waitcnt vmcnt(6)
	v_mul_f32_e32 v46, v15, v15
	v_mul_f32_e32 v47, v17, v17
	s_waitcnt vmcnt(5)
	v_mul_f32_e32 v48, v33, v33
	v_mul_f32_e32 v49, v35, v35
	s_waitcnt vmcnt(4)
	v_mul_f32_e32 v50, v11, v11
	v_mul_f32_e32 v51, v13, v13
	s_waitcnt vmcnt(3)
	v_mul_f32_e32 v52, v37, v37
	v_mul_f32_e32 v53, v39, v39
	s_waitcnt vmcnt(2)
	v_mul_f32_e32 v54, v7, v7
	v_mul_f32_e32 v55, v9, v9
	v_fmac_f32_e32 v44, v28, v28
	v_fmac_f32_e32 v45, v30, v30
	v_fmac_f32_e32 v46, v14, v14
	v_fmac_f32_e32 v47, v16, v16
	v_fmac_f32_e32 v48, v32, v32
	v_fmac_f32_e32 v49, v34, v34
	v_fmac_f32_e32 v50, v10, v10
	v_fmac_f32_e32 v51, v12, v12
	s_waitcnt vmcnt(1)
	v_mul_f32_e32 v56, v41, v41
	v_mul_f32_e32 v57, v43, v43
	s_waitcnt vmcnt(0)
	v_mul_f32_e32 v58, v3, v3
	v_mul_f32_e32 v59, v5, v5
	v_fmac_f32_e32 v52, v36, v36
	v_fmac_f32_e32 v53, v38, v38
	v_fmac_f32_e32 v54, v6, v6
	v_fmac_f32_e32 v55, v8, v8
	v_add_f32_e32 v44, v44, v45
	v_add_f32_e32 v45, v46, v47
	v_add_f32_e32 v46, v48, v49
	v_add_f32_e32 v47, v50, v51
	v_fmac_f32_e32 v56, v40, v40
	v_fmac_f32_e32 v57, v42, v42
	v_fmac_f32_e32 v58, v2, v2
	v_fmac_f32_e32 v59, v4, v4
	v_add_f32_e32 v48, v52, v53
	v_add_f32_e32 v49, v54, v55
	v_add_f32_e32 v44, v44, v46
	v_add_f32_e32 v45, v45, v47
	v_add_f32_e32 v50, v56, v57
	v_add_f32_e32 v51, v58, v59
	v_add_f32_e32 v44, v44, v48
	v_add_f32_e32 v45, v45, v49
	v_add_f32_e32 v44, v44, v50
	v_add_f32_e32 v45, v45, v51
	ds_bpermute_b32 v46, v22, v44
	ds_bpermute_b32 v47, v22, v45
	v_cvt_pk_bf16_f32 v28, v28, v29
	v_cvt_pk_bf16_f32 v29, v30, v31
	v_cvt_pk_bf16_f32 v30, v32, v33
	s_waitcnt lgkmcnt(1)
	v_add_f32_e32 v44, v44, v46
	s_waitcnt lgkmcnt(0)
	v_add_f32_e32 v45, v45, v47
	ds_bpermute_b32 v46, v23, v44
	ds_bpermute_b32 v47, v23, v45
	v_cvt_pk_bf16_f32 v31, v34, v35
	v_cvt_pk_bf16_f32 v32, v36, v37
	s_waitcnt lgkmcnt(1)
	v_add_f32_e32 v46, v44, v46
	s_waitcnt lgkmcnt(0)
	v_add_f32_e32 v47, v45, v47
	ds_bpermute_b32 v48, v24, v46
	ds_bpermute_b32 v49, v24, v47
	v_lshl_add_u64 v[44:45], v[18:19], 0, s[14:15]
	global_store_dwordx2 v[44:45], v[28:29], off
	global_store_dwordx2 v[44:45], v[30:31], off offset:512
	s_waitcnt lgkmcnt(1)
	v_add_f32_e32 v46, v46, v48
	s_waitcnt lgkmcnt(0)
	v_add_f32_e32 v47, v47, v49
	ds_bpermute_b32 v48, v25, v46
	ds_bpermute_b32 v49, v25, v47
	s_waitcnt lgkmcnt(1)
	v_add_f32_e32 v33, v46, v48
	s_waitcnt lgkmcnt(0)
	v_add_f32_e32 v34, v47, v49
	ds_bpermute_b32 v35, v26, v33
	ds_bpermute_b32 v46, v26, v34
	s_waitcnt lgkmcnt(1)
	v_add_f32_e32 v30, v33, v35
	s_waitcnt lgkmcnt(0)
	v_add_f32_e32 v28, v34, v46
	ds_bpermute_b32 v31, v27, v30
	ds_bpermute_b32 v29, v27, v28
	v_cvt_pk_bf16_f32 v33, v38, v39
	global_store_dwordx2 v[44:45], v[32:33], off offset:1024
	v_cvt_pk_bf16_f32 v32, v40, v41
	v_cvt_pk_bf16_f32 v33, v42, v43
	global_store_dwordx2 v[44:45], v[32:33], off offset:1536
	s_and_saveexec_b64 s[14:15], s[4:5]
	s_cbranch_execz .LBB0_387
	s_waitcnt lgkmcnt(1)
	v_add_f32_e32 v30, v30, v31
	v_cndmask_b32_e64 v32, 0, v30, s[6:7]
	v_lshl_add_u64 v[30:31], s[2:3], 4, v[20:21]
	global_store_dword v[30:31], v32, off
	s_or_b64 exec, exec, s[14:15]
	s_andn2_b64 vcc, exec, s[12:13]
	s_cbranch_vccnz .LBB0_379
	s_branch .LBB0_388
